# P5 norm fast path + EpiKV/EpiQ epilogue loads batched up front
# speedup vs baseline: 1.0001x; 1.0001x over previous
.LBB0_411:
	v_add_u32_e32 v68, s34, v166
	v_or_b32_e32 v0, v68, v158
	v_ashrrev_i32_e32 v1, 31, v0
	v_lshl_add_u64 v[70:71], v[0:1], 4, s[36:37]
	global_load_dwordx4 v[76:79], v[70:71], off
	global_load_dwordx4 v[80:83], v[70:71], off offset:256
	global_load_dwordx4 v[84:87], v[70:71], off offset:512
	global_load_dwordx4 v[88:91], v[70:71], off offset:768
	v_bfe_u32 v1, v157, 6, 1
	v_lshrrev_b32_e32 v2, 5, v164
	v_and_or_b32 v70, v2, 2, v1
	v_and_b32_e32 v69, 64, v157
	v_cmp_ne_u32_e32 vcc, 0, v69
	v_mul_u32_u24_e32 v69, 0x2400, v70
	s_waitcnt vmcnt(3)
	v_add_f32_e32 v1, v76, v77
	v_add_f32_e32 v1, v78, v1
	v_add_f32_e32 v1, v79, v1
	v_fmamk_f32 v1, v1, 0x3b800000, v194
	v_mul_f32_e32 v2, 0x4b800000, v1
	v_cmp_gt_f32_e64 s[0:1], s98, v1
	s_nop 1
	v_cndmask_b32_e64 v1, v1, v2, s[0:1]
	v_rsq_f32_e32 v1, v1
	v_lshl_or_b32 v2, v158, 1, v69
	v_mul_f32_e32 v71, 0x45800000, v1
	v_cndmask_b32_e64 v1, v1, v71, s[0:1]
	s_movk_i32 s0, 0x240
	v_mul_f32_e32 v64, v64, v1
	v_mul_f32_e32 v65, v65, v1
	v_mad_u32_u24 v2, v159, s0, v2
	v_mul_f32_e32 v66, v66, v1
	v_mul_f32_e32 v67, v67, v1
	v_cvt_pk_bf16_f32 v64, v64, v65
	v_cvt_pk_bf16_f32 v65, v66, v67
	s_and_saveexec_b64 s[0:1], vcc
	s_xor_b64 s[0:1], exec, s[0:1]
	s_cbranch_execz .LBB0_413
	ds_write_b16 v2, v64
	ds_write_b16_d16_hi v2, v64 offset:144
	ds_write_b16 v2, v65 offset:288
	ds_write_b16_d16_hi v2, v65 offset:432

.LBB0_425:
	s_andn2_saveexec_b64 s[0:1], s[0:1]
	ds_write_b64 v66, v[52:53] offset:96
	s_or_b64 exec, exec, s[0:1]
	v_or_b32_e32 v52, 16, v0
	v_ashrrev_i32_e32 v53, 31, v52
	v_lshl_add_u64 v[52:53], v[52:53], 4, s[36:37]
	s_waitcnt vmcnt(2)
	v_add_f32_e32 v1, v80, v81
	v_add_f32_e32 v1, v82, v1
	v_add_f32_e32 v1, v83, v1
	v_fmamk_f32 v1, v1, 0x3b800000, v194
	v_mul_f32_e32 v52, 0x4b800000, v1
	v_cmp_gt_f32_e64 s[0:1], s98, v1
	s_nop 1
	v_cndmask_b32_e64 v1, v1, v52, s[0:1]
	v_rsq_f32_e32 v1, v1
	s_nop 0
	v_mul_f32_e32 v52, 0x45800000, v1
	v_cndmask_b32_e64 v1, v1, v52, s[0:1]
	v_mul_f32_e32 v48, v48, v1
	v_mul_f32_e32 v49, v49, v1
	v_mul_f32_e32 v50, v50, v1
	v_mul_f32_e32 v51, v51, v1
	v_cvt_pk_bf16_f32 v48, v48, v49
	v_cvt_pk_bf16_f32 v49, v50, v51
	s_and_saveexec_b64 s[0:1], vcc
	s_xor_b64 s[0:1], exec, s[0:1]
	s_cbranch_execz .LBB0_429
	ds_write_b16 v2, v48 offset:32
	ds_write_b16_d16_hi v2, v48 offset:176
	ds_write_b16 v2, v49 offset:320
	ds_write_b16_d16_hi v2, v49 offset:464

.LBB0_441:
	s_andn2_saveexec_b64 s[0:1], s[0:1]
	ds_write_b64 v66, v[36:37] offset:2400
	s_or_b64 exec, exec, s[0:1]
	v_or_b32_e32 v36, 32, v0
	v_ashrrev_i32_e32 v37, 31, v36
	v_lshl_add_u64 v[36:37], v[36:37], 4, s[36:37]
	s_waitcnt vmcnt(1)
	v_add_f32_e32 v1, v84, v85
	v_add_f32_e32 v1, v86, v1
	v_add_f32_e32 v1, v87, v1
	v_fmamk_f32 v1, v1, 0x3b800000, v194
	v_mul_f32_e32 v36, 0x4b800000, v1
	v_cmp_gt_f32_e64 s[0:1], s98, v1
	s_nop 1
	v_cndmask_b32_e64 v1, v1, v36, s[0:1]
	v_rsq_f32_e32 v1, v1
	s_nop 0
	v_mul_f32_e32 v36, 0x45800000, v1
	v_cndmask_b32_e64 v1, v1, v36, s[0:1]
	v_mul_f32_e32 v32, v32, v1
	v_mul_f32_e32 v33, v33, v1
	v_mul_f32_e32 v34, v34, v1
	v_mul_f32_e32 v35, v35, v1
	v_cvt_pk_bf16_f32 v32, v32, v33
	v_cvt_pk_bf16_f32 v33, v34, v35
	s_and_saveexec_b64 s[0:1], vcc
	s_xor_b64 s[0:1], exec, s[0:1]
	s_cbranch_execz .LBB0_445
	ds_write_b16 v2, v32 offset:64
	ds_write_b16_d16_hi v2, v32 offset:208
	ds_write_b16 v2, v33 offset:352
	ds_write_b16_d16_hi v2, v33 offset:496

.LBB0_457:
	s_andn2_saveexec_b64 s[0:1], s[0:1]
	ds_write_b64 v66, v[20:21] offset:4704
	s_or_b64 exec, exec, s[0:1]
	v_or_b32_e32 v0, 48, v0
	v_ashrrev_i32_e32 v1, 31, v0
	v_lshl_add_u64 v[0:1], v[0:1], 4, s[36:37]
	s_waitcnt vmcnt(0)
	v_add_f32_e32 v0, v88, v89
	v_add_f32_e32 v0, v90, v0
	v_add_f32_e32 v0, v91, v0
	v_fmamk_f32 v0, v0, 0x3b800000, v194
	v_mul_f32_e32 v1, 0x4b800000, v0
	v_cmp_gt_f32_e64 s[0:1], s98, v0
	s_nop 1
	v_cndmask_b32_e64 v0, v0, v1, s[0:1]
	v_rsq_f32_e32 v0, v0
	s_nop 0
	v_mul_f32_e32 v1, 0x45800000, v0
	v_cndmask_b32_e64 v20, v0, v1, s[0:1]
	v_mul_f32_e32 v0, v16, v20
	v_mul_f32_e32 v1, v17, v20
	v_mul_f32_e32 v16, v18, v20
	v_mul_f32_e32 v17, v19, v20
	v_cvt_pk_bf16_f32 v0, v0, v1
	v_cvt_pk_bf16_f32 v1, v16, v17
	s_and_saveexec_b64 s[0:1], vcc
	s_xor_b64 s[0:1], exec, s[0:1]
	s_cbranch_execz .LBB0_461
	ds_write_b16 v2, v0 offset:96
	ds_write_b16_d16_hi v2, v0 offset:240
	ds_write_b16 v2, v1 offset:384
	ds_write_b16_d16_hi v2, v1 offset:528

.LBB0_479:
	v_add_u32_e32 v70, s42, v156
	v_or_b32_e32 v68, v70, v148
	v_ashrrev_i32_e32 v69, 31, v68
	v_lshlrev_b64 v[72:73], 5, v[68:69]
	v_lshl_add_u64 v[72:73], s[38:39], 0, v[72:73]
	global_load_dwordx2 v[90:91], v[72:73], off offset:16
	global_load_dwordx4 v[92:95], v[72:73], off offset:0
	v_readlane_b32 s40, v236, 40
	v_readlane_b32 s41, v236, 41
	v_add_u32_e32 v166, s15, v68
	v_ashrrev_i32_e32 v167, 31, v166
	v_lshlrev_b64 v[166:167], 6, v[166:167]
	v_lshlrev_b32_e32 v164, 4, v149
	v_mov_b32_e32 v165, 0
	v_lshl_add_u64 v[160:161], s[40:41], 0, v[166:167]
	v_lshl_add_u64 v[162:163], s[2:3], 0, v[166:167]
	v_lshl_add_u64 v[160:161], v[160:161], 0, v[164:165]
	v_lshl_add_u64 v[162:163], v[162:163], 0, v[164:165]
	global_load_dwordx4 v[96:99], v[160:161], off
	global_load_dwordx4 v[100:103], v[162:163], off
	global_load_dwordx2 v[104:105], v[72:73], off offset:528
	global_load_dwordx4 v[106:109], v[72:73], off offset:512
	global_load_dwordx4 v[110:113], v[160:161], off offset:1024
	global_load_dwordx4 v[114:117], v[162:163], off offset:1024
	global_load_dwordx2 v[118:119], v[72:73], off offset:1040
	global_load_dwordx4 v[120:123], v[72:73], off offset:1024
	global_load_dwordx4 v[124:127], v[160:161], off offset:2048
	global_load_dwordx4 v[128:131], v[162:163], off offset:2048
	global_load_dwordx2 v[132:133], v[72:73], off offset:1552
	global_load_dwordx4 v[134:137], v[72:73], off offset:1536
	global_load_dwordx4 v[138:141], v[160:161], off offset:3072
	global_load_dwordx4 v[142:145], v[162:163], off offset:3072
	v_lshrrev_b32_e32 v1, 5, v155
	v_bfe_u32 v2, v147, 6, 1
	v_and_or_b32 v1, v1, 2, v2
	v_readlane_b32 s40, v236, 40
	v_readlane_b32 s41, v236, 41
	v_and_or_b32 v0, v147, 64, s43
	v_lshrrev_b32_e32 v71, 4, v0
	s_movk_i32 s0, 0x2aab
	v_mul_u32_u24_e32 v1, 0x2400, v1
	v_lshlrev_b32_e32 v88, 3, v149
	s_add_i32 s34, s34, s33
	s_add_i32 s13, s13, s33
	s_waitcnt vmcnt(14)
	v_add_f32_e32 v2, v92, v93
	v_add_f32_e32 v2, v94, v2
	v_add_f32_e32 v2, v95, v2
	v_add_f32_e32 v2, v90, v2
	v_add_f32_e32 v2, v91, v2
	v_fmamk_f32 v2, v2, 0x3b2aaaab, v194
	v_cmp_gt_f32_e32 vcc, s98, v2
	v_mul_f32_e32 v69, 0x4b800000, v2
	v_add_u32_e32 v72, s15, v68
	v_cndmask_b32_e32 v2, v2, v69, vcc
	v_rsq_f32_e32 v2, v2
	v_ashrrev_i32_e32 v73, 31, v72
	v_lshlrev_b64 v[76:77], 6, v[72:73]
	v_lshl_add_u64 v[72:73], s[40:41], 0, v[76:77]
	v_mul_f32_e32 v69, 0x45800000, v2
	v_cndmask_b32_e32 v2, v2, v69, vcc
	v_mul_f32_e32 v80, 0x3e16c740, v2
	v_lshlrev_b32_e32 v2, 4, v149
	v_lshl_add_u64 v[76:77], s[2:3], 0, v[76:77]
	v_lshl_add_u64 v[72:73], v[72:73], 0, v[2:3]
	v_lshl_add_u64 v[76:77], v[76:77], 0, v[2:3]
	v_bfe_i32 v69, v0, 4, 16
	v_mul_i32_i24_e32 v69, 0x2aab, v69
	v_pk_mul_f32 v[54:55], v[54:55], v[80:81] op_sel_hi:[1,0]
	v_pk_mul_f32 v[52:53], v[52:53], v[80:81] op_sel_hi:[1,0]
	v_pk_mul_f32 v[56:57], v[56:57], v[80:81] op_sel_hi:[1,0]
	v_pk_mul_f32 v[58:59], v[58:59], v[80:81] op_sel_hi:[1,0]
	v_pk_mul_f32 v[62:63], v[62:63], v[80:81] op_sel_hi:[1,0]
	v_pk_mul_f32 v[60:61], v[60:61], v[80:81] op_sel_hi:[1,0]
	v_pk_mul_f32 v[66:67], v[66:67], v[80:81] op_sel_hi:[1,0]
	v_pk_mul_f32 v[64:65], v[64:65], v[80:81] op_sel_hi:[1,0]
	v_lshrrev_b32_e32 v80, 31, v69
	v_add_u16_sdwa v69, v69, v80 dst_sel:DWORD dst_unused:UNUSED_PAD src0_sel:WORD_1 src1_sel:DWORD
	v_mul_lo_u16_e32 v69, 6, v69
	v_sub_u16_e32 v69, v71, v69
	v_cmp_eq_u16_e32 vcc, 4, v69
	s_waitcnt vmcnt(13)
	v_pk_mul_f32 v[84:85], v[96:97], v[56:57]
	v_pk_mul_f32 v[86:87], v[98:99], v[58:59]
	s_waitcnt vmcnt(12)
	v_pk_mul_f32 v[82:83], v[100:101], v[56:57]
	v_pk_mul_f32 v[80:81], v[102:103], v[58:59]
	v_pk_fma_f32 v[82:83], v[96:97], v[52:53], v[82:83] neg_lo:[0,0,1] neg_hi:[0,0,1]
	v_pk_fma_f32 v[84:85], v[100:101], v[52:53], v[84:85]
	v_cndmask_b32_e32 v82, v52, v82, vcc
	v_or_b32_e32 v52, 2, v71
	v_pk_fma_f32 v[80:81], v[98:99], v[54:55], v[80:81] neg_lo:[0,0,1] neg_hi:[0,0,1]
	v_cndmask_b32_e32 v83, v53, v83, vcc
	v_mul_i32_i24_sdwa v53, sext(v52), s0 dst_sel:DWORD dst_unused:UNUSED_PAD src0_sel:WORD_0 src1_sel:DWORD
	v_pk_fma_f32 v[86:87], v[102:103], v[54:55], v[86:87]
	v_cndmask_b32_e32 v80, v54, v80, vcc
	v_lshrrev_b32_e32 v54, 31, v53
	v_add_u16_sdwa v53, v53, v54 dst_sel:DWORD dst_unused:UNUSED_PAD src0_sel:WORD_1 src1_sel:DWORD
	v_mul_lo_u16_e32 v53, 6, v53
	v_sub_u16_e32 v52, v52, v53
	v_cmp_eq_u16_e64 s[42:43], 4, v52
	v_pk_mul_f32 v[52:53], v[100:101], v[64:65]
	v_cndmask_b32_e32 v69, v58, v86, vcc
	v_cndmask_b32_e32 v86, v59, v87, vcc
	v_cndmask_b32_e32 v84, v56, v84, vcc
	v_cndmask_b32_e32 v85, v57, v85, vcc
	v_pk_fma_f32 v[52:53], v[96:97], v[60:61], v[52:53] neg_lo:[0,0,1] neg_hi:[0,0,1]
	v_pk_mul_f32 v[56:57], v[96:97], v[64:65]
	v_pk_mul_f32 v[58:59], v[98:99], v[66:67]
	v_cndmask_b32_e32 v81, v55, v81, vcc
	v_pk_mul_f32 v[54:55], v[102:103], v[66:67]
	v_pk_fma_f32 v[58:59], v[102:103], v[62:63], v[58:59]
	v_pk_fma_f32 v[56:57], v[100:101], v[60:61], v[56:57]
	v_cndmask_b32_e64 v60, v60, v52, s[42:43]
	v_mul_u32_u24_e32 v52, 0x90, v148
	v_pk_fma_f32 v[54:55], v[98:99], v[62:63], v[54:55] neg_lo:[0,0,1] neg_hi:[0,0,1]
	v_cndmask_b32_e64 v58, v66, v58, s[42:43]
	v_cndmask_b32_e64 v65, v65, v57, s[42:43]
	v_add3_u32 v52, v1, v52, v88
	v_cvt_pk_bf16_f32 v57, v69, v86
	v_cndmask_b32_e64 v59, v67, v59, s[42:43]
	v_cndmask_b32_e64 v64, v64, v56, s[42:43]
	v_cndmask_b32_e64 v62, v62, v54, s[42:43]
	v_cndmask_b32_e64 v63, v63, v55, s[42:43]
	v_cvt_pk_bf16_f32 v54, v82, v83
	v_cvt_pk_bf16_f32 v55, v80, v81
	v_cvt_pk_bf16_f32 v56, v84, v85
	ds_write2_b64 v52, v[54:55], v[56:57] offset1:4
	v_cvt_pk_bf16_f32 v57, v58, v59
	v_or_b32_e32 v58, 16, v68
	v_cndmask_b32_e64 v53, v61, v53, s[42:43]
	v_cvt_pk_bf16_f32 v54, v60, v53
	v_cvt_pk_bf16_f32 v55, v62, v63
	v_ashrrev_i32_e32 v59, 31, v58
	v_cvt_pk_bf16_f32 v56, v64, v65
	ds_write2_b64 v52, v[54:55], v[56:57] offset0:8 offset1:12
	v_lshlrev_b64 v[54:55], 5, v[58:59]
	v_lshl_add_u64 v[54:55], s[38:39], 0, v[54:55]
	s_waitcnt vmcnt(10)
	v_add_f32_e32 v53, v106, v107
	v_add_f32_e32 v53, v108, v53
	v_add_f32_e32 v53, v109, v53
	v_add_f32_e32 v53, v104, v53
	v_add_f32_e32 v53, v105, v53
	v_fmamk_f32 v53, v53, 0x3b2aaaab, v194
	v_cmp_gt_f32_e64 s[0:1], s98, v53
	v_mul_f32_e32 v54, 0x4b800000, v53
	s_nop 0
	v_cndmask_b32_e64 v53, v53, v54, s[0:1]
	v_rsq_f32_e32 v53, v53
	s_nop 0
	v_mul_f32_e32 v54, 0x45800000, v53
	v_cndmask_b32_e64 v53, v53, v54, s[0:1]
	v_add_u32_e32 v54, s15, v58
	v_ashrrev_i32_e32 v55, 31, v54
	v_lshlrev_b64 v[58:59], 6, v[54:55]
	v_lshl_add_u64 v[54:55], s[40:41], 0, v[58:59]
	v_lshl_add_u64 v[58:59], s[2:3], 0, v[58:59]
	v_lshl_add_u64 v[54:55], v[54:55], 0, v[2:3]
	v_lshl_add_u64 v[58:59], v[58:59], 0, v[2:3]
	v_mul_f32_e32 v62, 0x3e16c740, v53
	v_pk_mul_f32 v[40:41], v[40:41], v[62:63] op_sel_hi:[1,0]
	v_pk_mul_f32 v[42:43], v[42:43], v[62:63] op_sel_hi:[1,0]
	v_pk_mul_f32 v[38:39], v[38:39], v[62:63] op_sel_hi:[1,0]
	v_pk_mul_f32 v[36:37], v[36:37], v[62:63] op_sel_hi:[1,0]
	v_pk_mul_f32 v[46:47], v[46:47], v[62:63] op_sel_hi:[1,0]
	v_pk_mul_f32 v[44:45], v[44:45], v[62:63] op_sel_hi:[1,0]
	v_pk_mul_f32 v[50:51], v[50:51], v[62:63] op_sel_hi:[1,0]
	v_pk_mul_f32 v[48:49], v[48:49], v[62:63] op_sel_hi:[1,0]
	s_waitcnt vmcnt(9)
	v_pk_mul_f32 v[66:67], v[110:111], v[40:41]
	v_pk_mul_f32 v[72:73], v[112:113], v[42:43]
	s_waitcnt vmcnt(8)
	v_pk_mul_f32 v[62:63], v[116:117], v[42:43]
	v_pk_mul_f32 v[64:65], v[114:115], v[40:41]
	v_pk_fma_f32 v[62:63], v[112:113], v[38:39], v[62:63] neg_lo:[0,0,1] neg_hi:[0,0,1]
	v_pk_fma_f32 v[66:67], v[114:115], v[36:37], v[66:67]
	v_pk_fma_f32 v[64:65], v[110:111], v[36:37], v[64:65] neg_lo:[0,0,1] neg_hi:[0,0,1]
	v_pk_fma_f32 v[72:73], v[116:117], v[38:39], v[72:73]
	v_cndmask_b32_e32 v66, v40, v66, vcc
	v_cndmask_b32_e32 v67, v41, v67, vcc
	v_cndmask_b32_e32 v62, v38, v62, vcc
	v_cndmask_b32_e32 v63, v39, v63, vcc
	v_pk_mul_f32 v[38:39], v[116:117], v[50:51]
	v_pk_mul_f32 v[40:41], v[110:111], v[48:49]
	v_cndmask_b32_e32 v53, v42, v72, vcc
	v_cndmask_b32_e32 v69, v43, v73, vcc
	v_cndmask_b32_e32 v64, v36, v64, vcc
	v_cndmask_b32_e32 v65, v37, v65, vcc
	v_pk_mul_f32 v[36:37], v[114:115], v[48:49]
	v_pk_fma_f32 v[38:39], v[112:113], v[46:47], v[38:39] neg_lo:[0,0,1] neg_hi:[0,0,1]
	v_pk_mul_f32 v[42:43], v[112:113], v[50:51]
	v_pk_fma_f32 v[40:41], v[114:115], v[44:45], v[40:41]
	v_pk_fma_f32 v[36:37], v[110:111], v[44:45], v[36:37] neg_lo:[0,0,1] neg_hi:[0,0,1]
	v_pk_fma_f32 v[42:43], v[116:117], v[46:47], v[42:43]
	v_cndmask_b32_e64 v40, v48, v40, s[42:43]
	v_cndmask_b32_e64 v46, v46, v38, s[42:43]
	v_cvt_pk_bf16_f32 v38, v66, v67
	v_add_u32_e32 v48, 0x800, v52
	v_cndmask_b32_e64 v41, v49, v41, s[42:43]
	v_cndmask_b32_e64 v47, v47, v39, s[42:43]
	v_cndmask_b32_e64 v44, v44, v36, s[42:43]
	v_cndmask_b32_e64 v45, v45, v37, s[42:43]
	v_cvt_pk_bf16_f32 v36, v64, v65
	v_cvt_pk_bf16_f32 v37, v62, v63
	v_cvt_pk_bf16_f32 v39, v53, v69
	ds_write2_b64 v48, v[36:37], v[38:39] offset0:32 offset1:36
	v_cvt_pk_bf16_f32 v38, v40, v41
	v_or_b32_e32 v40, 32, v68
	v_cvt_pk_bf16_f32 v36, v44, v45
	v_cvt_pk_bf16_f32 v37, v46, v47
	v_ashrrev_i32_e32 v41, 31, v40
	v_cndmask_b32_e64 v42, v50, v42, s[42:43]
	v_cndmask_b32_e64 v43, v51, v43, s[42:43]
	v_cvt_pk_bf16_f32 v39, v42, v43
	ds_write2_b64 v48, v[36:37], v[38:39] offset0:40 offset1:44
	v_lshlrev_b64 v[36:37], 5, v[40:41]
	v_lshl_add_u64 v[36:37], s[38:39], 0, v[36:37]
	s_waitcnt vmcnt(6)
	v_add_f32_e32 v36, v120, v121
	v_add_f32_e32 v36, v122, v36
	v_add_f32_e32 v36, v123, v36
	v_add_f32_e32 v36, v118, v36
	v_add_f32_e32 v36, v119, v36
	v_fmamk_f32 v36, v36, 0x3b2aaaab, v194
	v_cmp_gt_f32_e64 s[0:1], s98, v36
	v_mul_f32_e32 v37, 0x4b800000, v36
	s_nop 0
	v_cndmask_b32_e64 v36, v36, v37, s[0:1]
	v_rsq_f32_e32 v36, v36
	s_nop 0
	v_mul_f32_e32 v37, 0x45800000, v36
	v_cndmask_b32_e64 v36, v36, v37, s[0:1]
	v_mul_f32_e32 v44, 0x3e16c740, v36
	v_add_u32_e32 v36, s15, v40
	v_ashrrev_i32_e32 v37, 31, v36
	v_lshlrev_b64 v[40:41], 6, v[36:37]
	v_lshl_add_u64 v[36:37], s[40:41], 0, v[40:41]
	v_lshl_add_u64 v[40:41], s[2:3], 0, v[40:41]
	v_lshl_add_u64 v[36:37], v[36:37], 0, v[2:3]
	v_lshl_add_u64 v[40:41], v[40:41], 0, v[2:3]
	v_pk_mul_f32 v[24:25], v[24:25], v[44:45] op_sel_hi:[1,0]
	v_pk_mul_f32 v[26:27], v[26:27], v[44:45] op_sel_hi:[1,0]
	v_pk_mul_f32 v[22:23], v[22:23], v[44:45] op_sel_hi:[1,0]
	v_pk_mul_f32 v[20:21], v[20:21], v[44:45] op_sel_hi:[1,0]
	v_pk_mul_f32 v[30:31], v[30:31], v[44:45] op_sel_hi:[1,0]
	v_pk_mul_f32 v[28:29], v[28:29], v[44:45] op_sel_hi:[1,0]
	v_pk_mul_f32 v[34:35], v[34:35], v[44:45] op_sel_hi:[1,0]
	v_pk_mul_f32 v[32:33], v[32:33], v[44:45] op_sel_hi:[1,0]
	s_waitcnt vmcnt(5)
	v_pk_mul_f32 v[48:49], v[124:125], v[24:25]
	v_pk_mul_f32 v[50:51], v[126:127], v[26:27]
	s_waitcnt vmcnt(4)
	v_pk_mul_f32 v[44:45], v[130:131], v[26:27]
	v_pk_mul_f32 v[46:47], v[128:129], v[24:25]
	v_pk_fma_f32 v[44:45], v[126:127], v[22:23], v[44:45] neg_lo:[0,0,1] neg_hi:[0,0,1]
	v_pk_fma_f32 v[48:49], v[128:129], v[20:21], v[48:49]
	v_pk_fma_f32 v[46:47], v[124:125], v[20:21], v[46:47] neg_lo:[0,0,1] neg_hi:[0,0,1]
	v_pk_fma_f32 v[50:51], v[130:131], v[22:23], v[50:51]
	v_cndmask_b32_e32 v48, v24, v48, vcc
	v_cndmask_b32_e32 v49, v25, v49, vcc
	v_cndmask_b32_e32 v44, v22, v44, vcc
	v_cndmask_b32_e32 v45, v23, v45, vcc
	v_pk_mul_f32 v[22:23], v[130:131], v[34:35]
	v_pk_mul_f32 v[24:25], v[124:125], v[32:33]
	v_cndmask_b32_e32 v50, v26, v50, vcc
	v_cndmask_b32_e32 v51, v27, v51, vcc
	v_cndmask_b32_e32 v46, v20, v46, vcc
	v_cndmask_b32_e32 v47, v21, v47, vcc
	v_pk_mul_f32 v[20:21], v[128:129], v[32:33]
	v_pk_fma_f32 v[22:23], v[126:127], v[30:31], v[22:23] neg_lo:[0,0,1] neg_hi:[0,0,1]
	v_pk_mul_f32 v[26:27], v[126:127], v[34:35]
	v_pk_fma_f32 v[24:25], v[128:129], v[28:29], v[24:25]
	v_pk_fma_f32 v[20:21], v[124:125], v[28:29], v[20:21] neg_lo:[0,0,1] neg_hi:[0,0,1]
	v_pk_fma_f32 v[26:27], v[130:131], v[30:31], v[26:27]
	v_cndmask_b32_e64 v24, v32, v24, s[42:43]
	v_cndmask_b32_e64 v30, v30, v22, s[42:43]
	v_cvt_pk_bf16_f32 v22, v48, v49
	v_add_u32_e32 v32, 0x1000, v52
	v_cndmask_b32_e64 v25, v33, v25, s[42:43]
	v_cndmask_b32_e64 v31, v31, v23, s[42:43]
	v_cndmask_b32_e64 v28, v28, v20, s[42:43]
	v_cndmask_b32_e64 v29, v29, v21, s[42:43]
	v_cvt_pk_bf16_f32 v20, v46, v47
	v_cvt_pk_bf16_f32 v21, v44, v45
	v_cvt_pk_bf16_f32 v23, v50, v51
	ds_write2_b64 v32, v[20:21], v[22:23] offset0:64 offset1:68
	v_cvt_pk_bf16_f32 v22, v24, v25
	v_or_b32_e32 v24, 48, v68
	v_cvt_pk_bf16_f32 v20, v28, v29
	v_cvt_pk_bf16_f32 v21, v30, v31
	v_ashrrev_i32_e32 v25, 31, v24
	v_cndmask_b32_e64 v26, v34, v26, s[42:43]
	v_cndmask_b32_e64 v27, v35, v27, s[42:43]
	v_cvt_pk_bf16_f32 v23, v26, v27
	ds_write2_b64 v32, v[20:21], v[22:23] offset0:72 offset1:76
	v_lshlrev_b64 v[20:21], 5, v[24:25]
	v_lshl_add_u64 v[20:21], s[38:39], 0, v[20:21]
	s_waitcnt vmcnt(2)
	v_add_f32_e32 v20, v134, v135
	v_add_f32_e32 v20, v136, v20
	v_add_f32_e32 v20, v137, v20
	v_add_f32_e32 v20, v132, v20
	v_add_f32_e32 v20, v133, v20
	v_fmamk_f32 v20, v20, 0x3b2aaaab, v194
	v_cmp_gt_f32_e64 s[0:1], s98, v20
	v_mul_f32_e32 v21, 0x4b800000, v20
	s_nop 0
	v_cndmask_b32_e64 v20, v20, v21, s[0:1]
	v_rsq_f32_e32 v20, v20
	s_nop 0
	v_mul_f32_e32 v21, 0x45800000, v20
	v_cndmask_b32_e64 v20, v20, v21, s[0:1]
	v_mul_f32_e32 v28, 0x3e16c740, v20
	v_add_u32_e32 v20, s15, v24
	v_ashrrev_i32_e32 v21, 31, v20
	v_lshlrev_b64 v[24:25], 6, v[20:21]
	v_lshl_add_u64 v[20:21], s[40:41], 0, v[24:25]
	v_lshl_add_u64 v[24:25], s[2:3], 0, v[24:25]
	v_lshl_add_u64 v[20:21], v[20:21], 0, v[2:3]
	v_lshl_add_u64 v[24:25], v[24:25], 0, v[2:3]
	v_pk_mul_f32 v[8:9], v[8:9], v[28:29] op_sel_hi:[1,0]
	v_pk_mul_f32 v[10:11], v[10:11], v[28:29] op_sel_hi:[1,0]
	v_pk_mul_f32 v[6:7], v[6:7], v[28:29] op_sel_hi:[1,0]
	v_pk_mul_f32 v[4:5], v[4:5], v[28:29] op_sel_hi:[1,0]
	v_pk_mul_f32 v[14:15], v[14:15], v[28:29] op_sel_hi:[1,0]
	v_pk_mul_f32 v[12:13], v[12:13], v[28:29] op_sel_hi:[1,0]
	v_pk_mul_f32 v[18:19], v[18:19], v[28:29] op_sel_hi:[1,0]
	v_pk_mul_f32 v[16:17], v[16:17], v[28:29] op_sel_hi:[1,0]
	s_movk_i32 s0, 0x90
	s_waitcnt vmcnt(1)
	v_pk_mul_f32 v[32:33], v[138:139], v[8:9]
	v_pk_mul_f32 v[34:35], v[140:141], v[10:11]
	s_waitcnt vmcnt(0)
	v_pk_mul_f32 v[28:29], v[144:145], v[10:11]
	v_pk_mul_f32 v[30:31], v[142:143], v[8:9]
	v_pk_fma_f32 v[28:29], v[140:141], v[6:7], v[28:29] neg_lo:[0,0,1] neg_hi:[0,0,1]
	v_pk_fma_f32 v[30:31], v[138:139], v[4:5], v[30:31] neg_lo:[0,0,1] neg_hi:[0,0,1]
	v_pk_fma_f32 v[34:35], v[144:145], v[6:7], v[34:35]
	v_pk_fma_f32 v[32:33], v[142:143], v[4:5], v[32:33]
	v_cndmask_b32_e32 v28, v6, v28, vcc
	v_cndmask_b32_e32 v29, v7, v29, vcc
	v_cndmask_b32_e32 v30, v4, v30, vcc
	v_cndmask_b32_e32 v31, v5, v31, vcc
	v_pk_mul_f32 v[4:5], v[142:143], v[16:17]
	v_pk_mul_f32 v[6:7], v[144:145], v[18:19]
	v_cndmask_b32_e32 v2, v10, v34, vcc
	v_cndmask_b32_e32 v34, v11, v35, vcc
	v_cndmask_b32_e32 v32, v8, v32, vcc
	v_cndmask_b32_e32 v33, v9, v33, vcc
	v_pk_fma_f32 v[6:7], v[140:141], v[14:15], v[6:7] neg_lo:[0,0,1] neg_hi:[0,0,1]
	v_pk_fma_f32 v[4:5], v[138:139], v[12:13], v[4:5] neg_lo:[0,0,1] neg_hi:[0,0,1]
	v_pk_mul_f32 v[8:9], v[138:139], v[16:17]
	v_pk_mul_f32 v[10:11], v[140:141], v[18:19]
	v_pk_fma_f32 v[8:9], v[142:143], v[12:13], v[8:9]
	v_pk_fma_f32 v[10:11], v[144:145], v[14:15], v[10:11]
	v_cndmask_b32_e64 v14, v14, v6, s[42:43]
	v_cndmask_b32_e64 v15, v15, v7, s[42:43]
	v_cndmask_b32_e64 v12, v12, v4, s[42:43]
	v_cndmask_b32_e64 v13, v13, v5, s[42:43]
	v_cvt_pk_bf16_f32 v4, v30, v31
	v_cvt_pk_bf16_f32 v5, v28, v29
	v_cvt_pk_bf16_f32 v6, v32, v33
	v_cvt_pk_bf16_f32 v7, v2, v34
	v_add_u32_e32 v2, 0x1800, v52
	v_cndmask_b32_e64 v10, v18, v10, s[42:43]
	v_cndmask_b32_e64 v11, v19, v11, s[42:43]
	v_cndmask_b32_e64 v8, v16, v8, s[42:43]
	v_cndmask_b32_e64 v9, v17, v9, s[42:43]
	ds_write2_b64 v2, v[4:5], v[6:7] offset0:96 offset1:100
	v_cvt_pk_bf16_f32 v4, v12, v13
	v_cvt_pk_bf16_f32 v5, v14, v15
	v_cvt_pk_bf16_f32 v6, v8, v9
	v_cvt_pk_bf16_f32 v7, v10, v11
	ds_write2_b64 v2, v[4:5], v[6:7] offset0:104 offset1:108
	v_lshlrev_b32_e32 v2, 4, v147
	v_and_b32_e32 v2, 0x70, v2
	v_or_b32_e32 v4, v1, v2
	v_mad_u32_u24 v12, v146, s0, v4
	v_readlane_b32 s0, v236, 58
	ds_read_b128 v[4:7], v12
	v_readlane_b32 s1, v236, 59
	v_ashrrev_i32_e32 v1, 31, v0
	v_or_b32_e32 v13, v70, v146
	v_mov_b64_e32 v[8:9], s[0:1]
	v_mad_i64_i32 v[10:11], s[0:1], v13, s79, v[8:9]
	v_lshlrev_b64 v[0:1], 1, v[0:1]
	v_lshl_add_u64 v[10:11], v[10:11], 0, v[0:1]
	v_lshl_add_u64 v[10:11], v[10:11], 0, v[2:3]
	s_waitcnt lgkmcnt(0)
	global_store_dwordx4 v[10:11], v[4:7], off
	ds_read_b128 v[4:7], v12 offset:1152
	v_or_b32_e32 v10, 8, v13
	v_mad_i64_i32 v[10:11], s[0:1], v10, s79, v[8:9]
	v_lshl_add_u64 v[10:11], v[10:11], 0, v[0:1]
	v_lshl_add_u64 v[10:11], v[10:11], 0, v[2:3]
	s_waitcnt lgkmcnt(0)
	global_store_dwordx4 v[10:11], v[4:7], off
	ds_read_b128 v[4:7], v12 offset:2304
	v_or_b32_e32 v10, 16, v13
	v_mad_i64_i32 v[10:11], s[0:1], v10, s79, v[8:9]
	v_lshl_add_u64 v[10:11], v[10:11], 0, v[0:1]
	v_lshl_add_u64 v[10:11], v[10:11], 0, v[2:3]
	s_waitcnt lgkmcnt(0)
	global_store_dwordx4 v[10:11], v[4:7], off
	ds_read_b128 v[4:7], v12 offset:3456
	v_or_b32_e32 v10, 24, v13
	v_mad_i64_i32 v[10:11], s[0:1], v10, s79, v[8:9]
	v_lshl_add_u64 v[10:11], v[10:11], 0, v[0:1]
	v_lshl_add_u64 v[10:11], v[10:11], 0, v[2:3]
	s_waitcnt lgkmcnt(0)
	global_store_dwordx4 v[10:11], v[4:7], off
	ds_read_b128 v[4:7], v12 offset:4608
	v_or_b32_e32 v10, 32, v13
	v_mad_i64_i32 v[10:11], s[0:1], v10, s79, v[8:9]
	v_lshl_add_u64 v[10:11], v[10:11], 0, v[0:1]
	v_lshl_add_u64 v[10:11], v[10:11], 0, v[2:3]
	s_waitcnt lgkmcnt(0)
	global_store_dwordx4 v[10:11], v[4:7], off
	ds_read_b128 v[4:7], v12 offset:5760
	v_or_b32_e32 v10, 40, v13
	v_mad_i64_i32 v[10:11], s[0:1], v10, s79, v[8:9]
	v_lshl_add_u64 v[10:11], v[10:11], 0, v[0:1]
	v_lshl_add_u64 v[10:11], v[10:11], 0, v[2:3]
	s_waitcnt lgkmcnt(0)
	global_store_dwordx4 v[10:11], v[4:7], off
	ds_read_b128 v[4:7], v12 offset:6912
	v_or_b32_e32 v10, 48, v13
	v_mad_i64_i32 v[10:11], s[0:1], v10, s79, v[8:9]
	v_lshl_add_u64 v[10:11], v[10:11], 0, v[0:1]
	v_lshl_add_u64 v[10:11], v[10:11], 0, v[2:3]
	s_waitcnt lgkmcnt(0)
	global_store_dwordx4 v[10:11], v[4:7], off
	ds_read_b128 v[4:7], v12 offset:8064
	v_or_b32_e32 v10, 56, v13
	v_mad_i64_i32 v[8:9], s[0:1], v10, s79, v[8:9]
	v_readlane_b32 s0, v235, 30
	v_lshl_add_u64 v[0:1], v[8:9], 0, v[0:1]
	s_add_i32 s12, s12, s0
	v_lshl_add_u64 v[0:1], v[0:1], 0, v[2:3]
	s_cmpk_gt_u32 s34, 0x5f
	s_waitcnt lgkmcnt(0)
	global_store_dwordx4 v[0:1], v[4:7], off
	s_barrier
	s_cbranch_scc1 .LBB0_329
